# GEMM k-step variant: LDS stores spread 2/3/3, barrier kept in front of the last MFMA group of each half
# baseline (speedup 1.0000x reference)
.LBB0_883:
	s_add_i32 s39, s39, 2
	v_lshl_add_u64 v[130:131], v[130:131], 0, s[4:5]
	s_andn2_b64 vcc, exec, s[6:7]
	v_lshl_add_u64 v[132:133], v[132:133], 0, s[4:5]
	s_waitcnt lgkmcnt(0)
	s_barrier
	v_mfma_f32_32x32x16_bf16 v[48:63], v[134:137], v[152:155], v[48:63]
	v_mfma_f32_32x32x16_bf16 v[32:47], v[134:137], v[156:159], v[32:47]
	v_mfma_f32_32x32x16_bf16 v[16:31], v[160:163], v[152:155], v[16:31]
	v_mfma_f32_32x32x16_bf16 v[0:15], v[160:163], v[156:159], v[0:15]
	s_cbranch_vccz .LBB0_890

.Lg1w_w1:
	ds_write_b128 v141, v[68:71] offset:32768
	ds_write_b128 v141, v[76:79] offset:49152
	v_add_u32_e32 v153, v148, v143
	s_waitcnt lgkmcnt(2)
	v_mfma_f32_32x32x16_bf16 v[16:31], v[162:165], v[158:161], v[16:31]
	s_cmp_gt_u32 s39, 12
	v_mfma_f32_32x32x16_bf16 v[48:63], v[154:157], v[158:161], v[48:63]
	v_mfma_f32_32x32x16_bf16 v[32:47], v[154:157], v[166:169], v[32:47]
	ds_read_b128 v[156:159], v153
	v_add_u32_e32 v154, v148, v145
	v_add_u32_e32 v155, v149, v143
	v_mfma_f32_32x32x16_bf16 v[0:15], v[162:165], v[166:169], v[0:15]
	ds_read_b128 v[160:163], v154 offset:16384
	ds_read_b128 v[164:167], v153 offset:4096
	ds_read_b128 v[168:171], v154 offset:20480
	ds_write_b128 v141, v[84:87] offset:36864
	ds_write_b128 v141, v[92:95] offset:53248
	ds_write_b128 v141, v[100:103] offset:40960
	s_waitcnt lgkmcnt(3)
	v_mfma_f32_32x32x16_bf16 v[48:63], v[156:159], v[160:163], v[48:63]
	v_mfma_f32_32x32x16_bf16 v[32:47], v[156:159], v[168:171], v[32:47]
	v_add_u32_e32 v156, v149, v145
	v_add_u32_e32 v157, v150, v143
	v_mfma_f32_32x32x16_bf16 v[16:31], v[164:167], v[160:163], v[16:31]
	ds_read_b128 v[158:161], v155
	v_mfma_f32_32x32x16_bf16 v[0:15], v[164:167], v[168:171], v[0:15]
	ds_read_b128 v[162:165], v156 offset:16384
	ds_read_b128 v[166:169], v155 offset:4096
	ds_read_b128 v[170:173], v156 offset:20480
	ds_write_b128 v141, v[108:111] offset:57344
	ds_write_b128 v141, v[116:119] offset:45056
	ds_write_b128 v141, v[124:127] offset:61440
	s_waitcnt lgkmcnt(3)
	v_mfma_f32_32x32x16_bf16 v[48:63], v[158:161], v[162:165], v[48:63]
	v_mfma_f32_32x32x16_bf16 v[32:47], v[158:161], v[170:173], v[32:47]
	v_add_u32_e32 v158, v150, v145
	v_mfma_f32_32x32x16_bf16 v[16:31], v[166:169], v[162:165], v[16:31]
	ds_read_b128 v[160:163], v157
	v_mfma_f32_32x32x16_bf16 v[0:15], v[166:169], v[170:173], v[0:15]
	ds_read_b128 v[164:167], v158 offset:16384
	ds_read_b128 v[168:171], v157 offset:4096
	ds_read_b128 v[172:175], v158 offset:20480
	s_waitcnt lgkmcnt(0)
	s_barrier
	v_mfma_f32_32x32x16_bf16 v[48:63], v[160:163], v[164:167], v[48:63]
	v_mfma_f32_32x32x16_bf16 v[32:47], v[160:163], v[172:175], v[32:47]
	v_mfma_f32_32x32x16_bf16 v[16:31], v[168:171], v[164:167], v[16:31]
	v_mfma_f32_32x32x16_bf16 v[0:15], v[168:171], v[172:175], v[0:15]
	ds_read_b128 v[160:163], v152 offset:49152
	ds_read_b128 v[164:167], v151 offset:36864
	ds_read_b128 v[168:171], v152 offset:53248
	s_cbranch_scc1 .LBB0_888
	v_add_co_u32_e32 v84, vcc, 0x10000, v136
	global_load_dwordx4 v[68:71], v[136:137], off offset:384
	global_load_dwordx4 v[76:79], v[134:135], off offset:384
	v_addc_co_u32_e32 v85, vcc, 0, v137, vcc
	v_add_co_u32_e32 v92, vcc, 0x10000, v134
	global_load_dwordx4 v[84:87], v[84:85], off offset:384
	s_nop 0
	v_addc_co_u32_e32 v93, vcc, 0, v135, vcc
	v_add_co_u32_e32 v100, vcc, 0x20000, v136
	global_load_dwordx4 v[92:95], v[92:93], off offset:384
	s_nop 0
	v_addc_co_u32_e32 v101, vcc, 0, v137, vcc
	v_add_co_u32_e32 v108, vcc, 0x20000, v134
	global_load_dwordx4 v[100:103], v[100:101], off offset:384
	s_nop 0
	v_addc_co_u32_e32 v109, vcc, 0, v135, vcc
	v_add_co_u32_e32 v116, vcc, 0x30000, v136
	global_load_dwordx4 v[108:111], v[108:109], off offset:384
	s_nop 0
	v_addc_co_u32_e32 v117, vcc, 0, v137, vcc
	v_add_co_u32_e32 v124, vcc, 0x30000, v134
	global_load_dwordx4 v[116:119], v[116:117], off offset:384
	s_nop 0
	v_addc_co_u32_e32 v125, vcc, 0, v135, vcc
	global_load_dwordx4 v[124:127], v[124:125], off offset:384
.LBB0_888:
	s_waitcnt vmcnt(8)
	ds_read_b128 v[134:137], v151 offset:32768
	ds_write_b128 v141, v[64:67]
	ds_write_b128 v141, v[72:75] offset:16384
	s_andn2_b64 vcc, exec, s[8:9]
	s_waitcnt lgkmcnt(2)
	v_mfma_f32_32x32x16_bf16 v[48:63], v[134:137], v[160:163], v[48:63]
	v_mfma_f32_32x32x16_bf16 v[32:47], v[134:137], v[168:171], v[32:47]
	v_mfma_f32_32x32x16_bf16 v[16:31], v[164:167], v[160:163], v[16:31]
	v_mfma_f32_32x32x16_bf16 v[0:15], v[164:167], v[168:171], v[0:15]
	ds_read_b128 v[134:137], v153 offset:32768
	ds_read_b128 v[160:163], v154 offset:49152
	ds_read_b128 v[164:167], v153 offset:36864
	ds_read_b128 v[168:171], v154 offset:53248
	ds_write_b128 v141, v[80:83] offset:4096
	ds_write_b128 v141, v[88:91] offset:20480
	ds_write_b128 v141, v[96:99] offset:8192
	s_waitcnt lgkmcnt(3)
	v_mfma_f32_32x32x16_bf16 v[48:63], v[134:137], v[160:163], v[48:63]
	v_mfma_f32_32x32x16_bf16 v[32:47], v[134:137], v[168:171], v[32:47]
	v_mfma_f32_32x32x16_bf16 v[16:31], v[164:167], v[160:163], v[16:31]
	v_mfma_f32_32x32x16_bf16 v[0:15], v[164:167], v[168:171], v[0:15]
	ds_read_b128 v[134:137], v155 offset:32768
	ds_read_b128 v[160:163], v156 offset:49152
	ds_read_b128 v[152:155], v155 offset:36864
	ds_read_b128 v[164:167], v156 offset:53248
	ds_write_b128 v141, v[104:107] offset:24576
	ds_write_b128 v141, v[112:115] offset:12288
	ds_write_b128 v141, v[120:123] offset:28672
	s_waitcnt lgkmcnt(3)
	v_mfma_f32_32x32x16_bf16 v[48:63], v[134:137], v[160:163], v[48:63]
	v_mfma_f32_32x32x16_bf16 v[32:47], v[134:137], v[164:167], v[32:47]
	v_mfma_f32_32x32x16_bf16 v[16:31], v[152:155], v[160:163], v[16:31]
	v_mfma_f32_32x32x16_bf16 v[0:15], v[152:155], v[164:167], v[0:15]
	ds_read_b128 v[134:137], v157 offset:32768
	ds_read_b128 v[152:155], v158 offset:49152
	ds_read_b128 v[160:163], v157 offset:36864
	ds_read_b128 v[156:159], v158 offset:53248
	s_branch .LBB0_883

.LBB0_1007:
	s_add_i32 s68, s68, 2
	v_lshl_add_u64 v[188:189], v[188:189], 0, s[52:53]
	s_andn2_b64 vcc, exec, s[0:1]
	v_lshl_add_u64 v[190:191], v[190:191], 0, s[52:53]
	s_waitcnt lgkmcnt(0)
	s_barrier
	v_mfma_f32_32x32x16_bf16 v[32:47], v[192:195], v[218:221], v[32:47]
	v_mfma_f32_32x32x16_bf16 v[48:63], v[192:195], v[226:229], v[48:63]
	v_mfma_f32_32x32x16_bf16 v[0:15], v[222:225], v[218:221], v[0:15]
	v_mfma_f32_32x32x16_bf16 v[16:31], v[222:225], v[226:229], v[16:31]
	s_cbranch_vccz .LBB0_1014

.Lkqw_w1:
	ds_write_b128 v135, v[68:71] offset:32768
	ds_write_b128 v135, v[76:79] offset:49152
	v_add_u32_e32 v157, v143, v139
	s_waitcnt lgkmcnt(2)
	v_mfma_f32_32x32x16_bf16 v[0:15], v[226:229], v[222:225], v[0:15]
	v_add_u32_e32 v159, v143, v141
	v_add_u32_e32 v161, v149, v139
	v_add_u32_e32 v163, v149, v141
	v_add_u32_e32 v165, v151, v139
	v_add_u32_e32 v167, v151, v141
	s_cmp_gt_u32 s68, 12
	v_mfma_f32_32x32x16_bf16 v[32:47], v[218:221], v[222:225], v[32:47]
	v_mfma_f32_32x32x16_bf16 v[48:63], v[218:221], v[230:233], v[48:63]
	ds_read_b128 v[218:221], v157
	v_mfma_f32_32x32x16_bf16 v[16:31], v[226:229], v[230:233], v[16:31]
	ds_read_b128 v[222:225], v159 offset:16384
	ds_read_b128 v[226:229], v157 offset:4096
	ds_read_b128 v[230:233], v159 offset:20480
	ds_write_b128 v135, v[84:87] offset:36864
	ds_write_b128 v135, v[92:95] offset:53248
	ds_write_b128 v135, v[100:103] offset:40960
	s_waitcnt lgkmcnt(3)
	v_mfma_f32_32x32x16_bf16 v[32:47], v[218:221], v[222:225], v[32:47]
	v_mfma_f32_32x32x16_bf16 v[48:63], v[218:221], v[230:233], v[48:63]
	ds_read_b128 v[218:221], v161
	v_mfma_f32_32x32x16_bf16 v[0:15], v[226:229], v[222:225], v[0:15]
	v_mfma_f32_32x32x16_bf16 v[16:31], v[226:229], v[230:233], v[16:31]
	ds_read_b128 v[222:225], v163 offset:16384
	ds_read_b128 v[226:229], v161 offset:4096
	ds_read_b128 v[230:233], v163 offset:20480
	ds_write_b128 v135, v[108:111] offset:57344
	ds_write_b128 v135, v[116:119] offset:45056
	ds_write_b128 v135, v[124:127] offset:61440
	s_waitcnt lgkmcnt(3)
	v_mfma_f32_32x32x16_bf16 v[32:47], v[218:221], v[222:225], v[32:47]
	v_mfma_f32_32x32x16_bf16 v[48:63], v[218:221], v[230:233], v[48:63]
	ds_read_b128 v[218:221], v165
	v_mfma_f32_32x32x16_bf16 v[0:15], v[226:229], v[222:225], v[0:15]
	v_mfma_f32_32x32x16_bf16 v[16:31], v[226:229], v[230:233], v[16:31]
	ds_read_b128 v[222:225], v167 offset:16384
	ds_read_b128 v[226:229], v165 offset:4096
	ds_read_b128 v[230:233], v167 offset:20480
	s_waitcnt lgkmcnt(0)
	s_barrier
	v_mfma_f32_32x32x16_bf16 v[32:47], v[218:221], v[222:225], v[32:47]
	v_mfma_f32_32x32x16_bf16 v[48:63], v[218:221], v[230:233], v[48:63]
	v_mfma_f32_32x32x16_bf16 v[0:15], v[226:229], v[222:225], v[0:15]
	v_mfma_f32_32x32x16_bf16 v[16:31], v[226:229], v[230:233], v[16:31]
	ds_read_b128 v[218:221], v155 offset:49152
	ds_read_b128 v[222:225], v153 offset:36864
	ds_read_b128 v[226:229], v155 offset:53248
	s_cbranch_scc1 .LBB0_1012
	v_add_co_u32_e32 v84, vcc, 0x10000, v194
	global_load_dwordx4 v[68:71], v[194:195], off offset:384
	global_load_dwordx4 v[76:79], v[192:193], off offset:384
	v_addc_co_u32_e32 v85, vcc, 0, v195, vcc
	v_add_co_u32_e32 v92, vcc, 0x10000, v192
	global_load_dwordx4 v[84:87], v[84:85], off offset:384
	s_nop 0
	v_addc_co_u32_e32 v93, vcc, 0, v193, vcc
	v_add_co_u32_e32 v100, vcc, 0x20000, v194
	global_load_dwordx4 v[92:95], v[92:93], off offset:384
	s_nop 0
	v_addc_co_u32_e32 v101, vcc, 0, v195, vcc
	v_add_co_u32_e32 v108, vcc, 0x20000, v192
	global_load_dwordx4 v[100:103], v[100:101], off offset:384
	s_nop 0
	v_addc_co_u32_e32 v109, vcc, 0, v193, vcc
	v_add_co_u32_e32 v116, vcc, 0x30000, v194
	global_load_dwordx4 v[108:111], v[108:109], off offset:384
	s_nop 0
	v_addc_co_u32_e32 v117, vcc, 0, v195, vcc
	v_add_co_u32_e32 v124, vcc, 0x30000, v192
	global_load_dwordx4 v[116:119], v[116:117], off offset:384
	s_nop 0
	v_addc_co_u32_e32 v125, vcc, 0, v193, vcc
	global_load_dwordx4 v[124:127], v[124:125], off offset:384
.LBB0_1012:
	s_waitcnt vmcnt(8)
	ds_read_b128 v[192:195], v153 offset:32768
	ds_write_b128 v135, v[64:67]
	ds_write_b128 v135, v[72:75] offset:16384
	s_andn2_b64 vcc, exec, s[8:9]
	s_waitcnt lgkmcnt(2)
	v_mfma_f32_32x32x16_bf16 v[32:47], v[192:195], v[218:221], v[32:47]
	v_mfma_f32_32x32x16_bf16 v[48:63], v[192:195], v[226:229], v[48:63]
	v_mfma_f32_32x32x16_bf16 v[0:15], v[222:225], v[218:221], v[0:15]
	v_mfma_f32_32x32x16_bf16 v[16:31], v[222:225], v[226:229], v[16:31]
	ds_read_b128 v[192:195], v157 offset:32768
	ds_read_b128 v[218:221], v159 offset:49152
	ds_read_b128 v[222:225], v157 offset:36864
	ds_read_b128 v[226:229], v159 offset:53248
	ds_write_b128 v135, v[80:83] offset:4096
	ds_write_b128 v135, v[88:91] offset:20480
	ds_write_b128 v135, v[96:99] offset:8192
	s_waitcnt lgkmcnt(3)
	v_mfma_f32_32x32x16_bf16 v[32:47], v[192:195], v[218:221], v[32:47]
	v_mfma_f32_32x32x16_bf16 v[48:63], v[192:195], v[226:229], v[48:63]
	v_mfma_f32_32x32x16_bf16 v[0:15], v[222:225], v[218:221], v[0:15]
	v_mfma_f32_32x32x16_bf16 v[16:31], v[222:225], v[226:229], v[16:31]
	ds_read_b128 v[192:195], v161 offset:32768
	ds_read_b128 v[218:221], v163 offset:49152
	ds_read_b128 v[222:225], v161 offset:36864
	ds_read_b128 v[226:229], v163 offset:53248
	ds_write_b128 v135, v[104:107] offset:24576
	ds_write_b128 v135, v[112:115] offset:12288
	ds_write_b128 v135, v[120:123] offset:28672
	s_waitcnt lgkmcnt(3)
	v_mfma_f32_32x32x16_bf16 v[32:47], v[192:195], v[218:221], v[32:47]
	v_mfma_f32_32x32x16_bf16 v[48:63], v[192:195], v[226:229], v[48:63]
	v_mfma_f32_32x32x16_bf16 v[0:15], v[222:225], v[218:221], v[0:15]
	v_mfma_f32_32x32x16_bf16 v[16:31], v[222:225], v[226:229], v[16:31]
	ds_read_b128 v[192:195], v165 offset:32768
	ds_read_b128 v[218:221], v167 offset:49152
	ds_read_b128 v[222:225], v165 offset:36864
	ds_read_b128 v[226:229], v167 offset:53248
	s_branch .LBB0_1007

.LBB0_1505:
	s_add_i32 s16, s16, 2
	v_lshl_add_u64 v[130:131], v[130:131], 0, s[2:3]
	s_andn2_b64 vcc, exec, s[4:5]
	v_lshl_add_u64 v[132:133], v[132:133], 0, s[2:3]
	s_waitcnt lgkmcnt(0)
	s_barrier
	v_mfma_f32_32x32x16_bf16 v[48:63], v[134:137], v[146:149], v[48:63]
	v_mfma_f32_32x32x16_bf16 v[32:47], v[134:137], v[150:153], v[32:47]
	v_mfma_f32_32x32x16_bf16 v[16:31], v[154:157], v[146:149], v[16:31]
	v_mfma_f32_32x32x16_bf16 v[0:15], v[154:157], v[150:153], v[0:15]
	s_cbranch_vccz .LBB0_1512

.Lg2w_w1:
	ds_write_b128 v138, v[68:71] offset:32768
	ds_write_b128 v138, v[76:79] offset:49152
	v_add_u32_e32 v147, v142, v140
	s_waitcnt lgkmcnt(2)
	v_mfma_f32_32x32x16_bf16 v[16:31], v[156:159], v[152:155], v[16:31]
	s_cmp_gt_u32 s16, 12
	v_mfma_f32_32x32x16_bf16 v[48:63], v[148:151], v[152:155], v[48:63]
	v_mfma_f32_32x32x16_bf16 v[32:47], v[148:151], v[160:163], v[32:47]
	ds_read_b128 v[150:153], v147
	v_add_u32_e32 v148, v142, v141
	v_add_u32_e32 v149, v143, v140
	v_mfma_f32_32x32x16_bf16 v[0:15], v[156:159], v[160:163], v[0:15]
	ds_read_b128 v[154:157], v148 offset:16384
	ds_read_b128 v[158:161], v147 offset:4096
	ds_read_b128 v[162:165], v148 offset:20480
	ds_write_b128 v138, v[84:87] offset:36864
	ds_write_b128 v138, v[92:95] offset:53248
	ds_write_b128 v138, v[100:103] offset:40960
	s_waitcnt lgkmcnt(3)
	v_mfma_f32_32x32x16_bf16 v[48:63], v[150:153], v[154:157], v[48:63]
	v_mfma_f32_32x32x16_bf16 v[32:47], v[150:153], v[162:165], v[32:47]
	v_add_u32_e32 v150, v143, v141
	v_add_u32_e32 v151, v144, v140
	v_mfma_f32_32x32x16_bf16 v[16:31], v[158:161], v[154:157], v[16:31]
	ds_read_b128 v[152:155], v149
	v_mfma_f32_32x32x16_bf16 v[0:15], v[158:161], v[162:165], v[0:15]
	ds_read_b128 v[156:159], v150 offset:16384
	ds_read_b128 v[160:163], v149 offset:4096
	ds_read_b128 v[170:173], v150 offset:20480
	ds_write_b128 v138, v[108:111] offset:57344
	ds_write_b128 v138, v[116:119] offset:45056
	ds_write_b128 v138, v[124:127] offset:61440
	s_waitcnt lgkmcnt(3)
	v_mfma_f32_32x32x16_bf16 v[48:63], v[152:155], v[156:159], v[48:63]
	v_mfma_f32_32x32x16_bf16 v[32:47], v[152:155], v[170:173], v[32:47]
	v_add_u32_e32 v152, v144, v141
	v_mfma_f32_32x32x16_bf16 v[16:31], v[160:163], v[156:159], v[16:31]
	ds_read_b128 v[154:157], v151
	v_mfma_f32_32x32x16_bf16 v[0:15], v[160:163], v[170:173], v[0:15]
	ds_read_b128 v[158:161], v152 offset:16384
	ds_read_b128 v[162:165], v151 offset:4096
	ds_read_b128 v[170:173], v152 offset:20480
	s_waitcnt lgkmcnt(0)
	s_barrier
	v_mfma_f32_32x32x16_bf16 v[48:63], v[154:157], v[158:161], v[48:63]
	v_mfma_f32_32x32x16_bf16 v[32:47], v[154:157], v[170:173], v[32:47]
	v_mfma_f32_32x32x16_bf16 v[16:31], v[162:165], v[158:161], v[16:31]
	v_mfma_f32_32x32x16_bf16 v[0:15], v[162:165], v[170:173], v[0:15]
	ds_read_b128 v[154:157], v146 offset:49152
	ds_read_b128 v[158:161], v145 offset:36864
	ds_read_b128 v[162:165], v146 offset:53248
	s_cbranch_scc1 .LBB0_1510
	v_add_co_u32_e32 v84, vcc, 0x10000, v136
	global_load_dwordx4 v[68:71], v[136:137], off offset:384
	global_load_dwordx4 v[76:79], v[134:135], off offset:384
	v_addc_co_u32_e32 v85, vcc, 0, v137, vcc
	v_add_co_u32_e32 v92, vcc, 0x10000, v134
	global_load_dwordx4 v[84:87], v[84:85], off offset:384
	s_nop 0
	v_addc_co_u32_e32 v93, vcc, 0, v135, vcc
	v_add_co_u32_e32 v100, vcc, 0x20000, v136
	global_load_dwordx4 v[92:95], v[92:93], off offset:384
	s_nop 0
	v_addc_co_u32_e32 v101, vcc, 0, v137, vcc
	v_add_co_u32_e32 v108, vcc, 0x20000, v134
	global_load_dwordx4 v[100:103], v[100:101], off offset:384
	s_nop 0
	v_addc_co_u32_e32 v109, vcc, 0, v135, vcc
	v_add_co_u32_e32 v116, vcc, 0x30000, v136
	global_load_dwordx4 v[108:111], v[108:109], off offset:384
	s_nop 0
	v_addc_co_u32_e32 v117, vcc, 0, v137, vcc
	v_add_co_u32_e32 v124, vcc, 0x30000, v134
	global_load_dwordx4 v[116:119], v[116:117], off offset:384
	s_nop 0
	v_addc_co_u32_e32 v125, vcc, 0, v135, vcc
	global_load_dwordx4 v[124:127], v[124:125], off offset:384
.LBB0_1510:
	s_waitcnt vmcnt(8)
	ds_read_b128 v[134:137], v145 offset:32768
	ds_write_b128 v138, v[64:67]
	ds_write_b128 v138, v[72:75] offset:16384
	s_andn2_b64 vcc, exec, s[6:7]
	s_waitcnt lgkmcnt(2)
	v_mfma_f32_32x32x16_bf16 v[48:63], v[134:137], v[154:157], v[48:63]
	v_mfma_f32_32x32x16_bf16 v[32:47], v[134:137], v[162:165], v[32:47]
	v_mfma_f32_32x32x16_bf16 v[16:31], v[158:161], v[154:157], v[16:31]
	v_mfma_f32_32x32x16_bf16 v[0:15], v[158:161], v[162:165], v[0:15]
	ds_read_b128 v[134:137], v147 offset:32768
	ds_read_b128 v[154:157], v148 offset:49152
	ds_read_b128 v[158:161], v147 offset:36864
	ds_read_b128 v[162:165], v148 offset:53248
	ds_write_b128 v138, v[80:83] offset:4096
	ds_write_b128 v138, v[88:91] offset:20480
	ds_write_b128 v138, v[96:99] offset:8192
	s_waitcnt lgkmcnt(3)
	v_mfma_f32_32x32x16_bf16 v[48:63], v[134:137], v[154:157], v[48:63]
	v_mfma_f32_32x32x16_bf16 v[32:47], v[134:137], v[162:165], v[32:47]
	v_mfma_f32_32x32x16_bf16 v[16:31], v[158:161], v[154:157], v[16:31]
	v_mfma_f32_32x32x16_bf16 v[0:15], v[158:161], v[162:165], v[0:15]
	ds_read_b128 v[134:137], v149 offset:32768
	ds_read_b128 v[154:157], v150 offset:49152
	ds_read_b128 v[146:149], v149 offset:36864
	ds_read_b128 v[158:161], v150 offset:53248
	ds_write_b128 v138, v[104:107] offset:24576
	ds_write_b128 v138, v[112:115] offset:12288
	ds_write_b128 v138, v[120:123] offset:28672
	s_waitcnt lgkmcnt(3)
	v_mfma_f32_32x32x16_bf16 v[48:63], v[134:137], v[154:157], v[48:63]
	v_mfma_f32_32x32x16_bf16 v[32:47], v[134:137], v[158:161], v[32:47]
	v_mfma_f32_32x32x16_bf16 v[16:31], v[146:149], v[154:157], v[16:31]
	v_mfma_f32_32x32x16_bf16 v[0:15], v[146:149], v[158:161], v[0:15]
	ds_read_b128 v[134:137], v151 offset:32768
	ds_read_b128 v[146:149], v152 offset:49152
	ds_read_b128 v[154:157], v151 offset:36864
	ds_read_b128 v[150:153], v152 offset:53248
	s_branch .LBB0_1505
